# stack2: + P1 conv-input/q epilogue with 8 cols per lane (dwordx4 stores), bias loaded once per half
# speedup vs baseline: 1.0212x; 1.0077x over previous
; DI unsigned pack2(float a, float b) { const f32x2 v = {a, b}; const bf16x2_t r = __builtin_convertvector(v, bf16x2_t); return __builtin_bit_cast(unsigned, r); }
; DI void inproj_epilogue(const Params& p, const char* smem, const int m0, const int n0) {
;     ...
;   if (n0 < 1536) {
;     u16* dst = n0 < 1024 ? (pu + (size_t)m0 * 1024 + n0) : (qb + (size_t)m0 * 512 + (n0 - 1024));
;     const int ld = n0 < 1024 ? 1024 : 512;
; #pragma unroll 4
;     for (int i = 0; i < 16; ++i) {
;       const int c = threadIdx.x + NT * i, row = c >> 5, ch = c & 31;
;       const float4 y = *(const float4*)(ct + row * CT_PITCH + 4 * ch), bv = *(const float4*)(p.b_in + n0 + 4 * ch);
;       uint2 r; r.x = pack2(y.x + bv.x, y.y + bv.y); r.y = pack2(y.z + bv.z, y.w + bv.w);
;       *(uint2*)(dst + (size_t)row * ld + 4 * ch) = r;
;     }
.LBB0_86:
	v_lshrrev_b32_e32 v228, 4, v0
	v_and_b32_e32 v229, 15, v0
	v_mul_lo_u32 v227, v228, s84
	v_lshlrev_b32_e32 v226, 5, v229
	v_mul_u32_u24_e32 v228, 0x210, v228
	v_lshlrev_b32_e32 v227, 1, v227
	v_add_u32_e32 v226, v228, v226
	v_lshl_add_u32 v227, v229, 4, v227
	v_lshl_add_u32 v228, v229, 3, s78
	v_lshlrev_b32_e32 v228, 2, v228
	global_load_dwordx4 v[248:251], v228, s[56:57]
	global_load_dwordx4 v[252:255], v228, s[56:57] offset:16
	s_mov_b64 s[98:99], s[82:83]
	s_lshl_b32 s100, s84, 6
	ds_read_b128 v[240:243], v226
	ds_read_b128 v[244:247], v226 offset:16
	s_waitcnt vmcnt(0)
	s_waitcnt lgkmcnt(0)
	v_pk_add_f32 v[240:241], v[240:241], v[248:249]
	v_pk_add_f32 v[242:243], v[242:243], v[250:251]
	v_pk_add_f32 v[244:245], v[244:245], v[252:253]
	v_pk_add_f32 v[246:247], v[246:247], v[254:255]
	v_cvt_pk_bf16_f32 v230, v240, v241
	v_cvt_pk_bf16_f32 v231, v242, v243
	v_cvt_pk_bf16_f32 v232, v244, v245
	v_cvt_pk_bf16_f32 v233, v246, v247
	v_add_u32_e32 v226, 0x4200, v226
	ds_read_b128 v[240:243], v226
	ds_read_b128 v[244:247], v226 offset:16
	global_store_dwordx4 v227, v[230:233], s[98:99]
	s_add_u32 s98, s98, s100
	s_addc_u32 s99, s99, 0
	s_waitcnt lgkmcnt(0)
	v_pk_add_f32 v[240:241], v[240:241], v[248:249]
	v_pk_add_f32 v[242:243], v[242:243], v[250:251]
	v_pk_add_f32 v[244:245], v[244:245], v[252:253]
	v_pk_add_f32 v[246:247], v[246:247], v[254:255]
	v_cvt_pk_bf16_f32 v234, v240, v241
	v_cvt_pk_bf16_f32 v235, v242, v243
	v_cvt_pk_bf16_f32 v236, v244, v245
	v_cvt_pk_bf16_f32 v237, v246, v247
	v_add_u32_e32 v226, 0x4200, v226
	ds_read_b128 v[240:243], v226
	ds_read_b128 v[244:247], v226 offset:16
	global_store_dwordx4 v227, v[234:237], s[98:99]
	s_add_u32 s98, s98, s100
	s_addc_u32 s99, s99, 0
	s_waitcnt lgkmcnt(0)
	v_pk_add_f32 v[240:241], v[240:241], v[248:249]
	v_pk_add_f32 v[242:243], v[242:243], v[250:251]
	v_pk_add_f32 v[244:245], v[244:245], v[252:253]
	v_pk_add_f32 v[246:247], v[246:247], v[254:255]
	v_cvt_pk_bf16_f32 v230, v240, v241
	v_cvt_pk_bf16_f32 v231, v242, v243
	v_cvt_pk_bf16_f32 v232, v244, v245
	v_cvt_pk_bf16_f32 v233, v246, v247
	v_add_u32_e32 v226, 0x4200, v226
	ds_read_b128 v[240:243], v226
	ds_read_b128 v[244:247], v226 offset:16
	global_store_dwordx4 v227, v[230:233], s[98:99]
	s_add_u32 s98, s98, s100
	s_addc_u32 s99, s99, 0
	s_waitcnt lgkmcnt(0)
	v_pk_add_f32 v[240:241], v[240:241], v[248:249]
	v_pk_add_f32 v[242:243], v[242:243], v[250:251]
	v_pk_add_f32 v[244:245], v[244:245], v[252:253]
	v_pk_add_f32 v[246:247], v[246:247], v[254:255]
	v_cvt_pk_bf16_f32 v234, v240, v241
	v_cvt_pk_bf16_f32 v235, v242, v243
	v_cvt_pk_bf16_f32 v236, v244, v245
	v_cvt_pk_bf16_f32 v237, v246, v247
	v_add_u32_e32 v226, 0x4200, v226
	ds_read_b128 v[240:243], v226
	ds_read_b128 v[244:247], v226 offset:16
	global_store_dwordx4 v227, v[234:237], s[98:99]
	s_add_u32 s98, s98, s100
	s_addc_u32 s99, s99, 0
	s_waitcnt lgkmcnt(0)
	v_pk_add_f32 v[240:241], v[240:241], v[248:249]
	v_pk_add_f32 v[242:243], v[242:243], v[250:251]
	v_pk_add_f32 v[244:245], v[244:245], v[252:253]
	v_pk_add_f32 v[246:247], v[246:247], v[254:255]
	v_cvt_pk_bf16_f32 v230, v240, v241
	v_cvt_pk_bf16_f32 v231, v242, v243
	v_cvt_pk_bf16_f32 v232, v244, v245
	v_cvt_pk_bf16_f32 v233, v246, v247
	v_add_u32_e32 v226, 0x4200, v226
	ds_read_b128 v[240:243], v226
	ds_read_b128 v[244:247], v226 offset:16
	global_store_dwordx4 v227, v[230:233], s[98:99]
	s_add_u32 s98, s98, s100
	s_addc_u32 s99, s99, 0
	s_waitcnt lgkmcnt(0)
	v_pk_add_f32 v[240:241], v[240:241], v[248:249]
	v_pk_add_f32 v[242:243], v[242:243], v[250:251]
	v_pk_add_f32 v[244:245], v[244:245], v[252:253]
	v_pk_add_f32 v[246:247], v[246:247], v[254:255]
	v_cvt_pk_bf16_f32 v234, v240, v241
	v_cvt_pk_bf16_f32 v235, v242, v243
	v_cvt_pk_bf16_f32 v236, v244, v245
	v_cvt_pk_bf16_f32 v237, v246, v247
	v_add_u32_e32 v226, 0x4200, v226
	ds_read_b128 v[240:243], v226
	ds_read_b128 v[244:247], v226 offset:16
	global_store_dwordx4 v227, v[234:237], s[98:99]
	s_add_u32 s98, s98, s100
	s_addc_u32 s99, s99, 0
	s_waitcnt lgkmcnt(0)
	v_pk_add_f32 v[240:241], v[240:241], v[248:249]
	v_pk_add_f32 v[242:243], v[242:243], v[250:251]
	v_pk_add_f32 v[244:245], v[244:245], v[252:253]
	v_pk_add_f32 v[246:247], v[246:247], v[254:255]
	v_cvt_pk_bf16_f32 v230, v240, v241
	v_cvt_pk_bf16_f32 v231, v242, v243
	v_cvt_pk_bf16_f32 v232, v244, v245
	v_cvt_pk_bf16_f32 v233, v246, v247
	v_add_u32_e32 v226, 0x4200, v226
	ds_read_b128 v[240:243], v226
	ds_read_b128 v[244:247], v226 offset:16
	global_store_dwordx4 v227, v[230:233], s[98:99]
	s_add_u32 s98, s98, s100
	s_addc_u32 s99, s99, 0
	s_waitcnt lgkmcnt(0)
	v_pk_add_f32 v[240:241], v[240:241], v[248:249]
	v_pk_add_f32 v[242:243], v[242:243], v[250:251]
	v_pk_add_f32 v[244:245], v[244:245], v[252:253]
	v_pk_add_f32 v[246:247], v[246:247], v[254:255]
	v_cvt_pk_bf16_f32 v234, v240, v241
	v_cvt_pk_bf16_f32 v235, v242, v243
	v_cvt_pk_bf16_f32 v236, v244, v245
	v_cvt_pk_bf16_f32 v237, v246, v247
	global_store_dwordx4 v227, v[234:237], s[98:99]

; DI unsigned pack2(float a, float b) { const f32x2 v = {a, b}; const bf16x2_t r = __builtin_convertvector(v, bf16x2_t); return __builtin_bit_cast(unsigned, r); }
; DI void inproj_epilogue(const Params& p, const char* smem, const int m0, const int n0) {
;     ...
;   if (n0 < 1536) {
;     u16* dst = n0 < 1024 ? (pu + (size_t)m0 * 1024 + n0) : (qb + (size_t)m0 * 512 + (n0 - 1024));
;     const int ld = n0 < 1024 ? 1024 : 512;
; #pragma unroll 4
;     for (int i = 0; i < 16; ++i) {
;       const int c = threadIdx.x + NT * i, row = c >> 5, ch = c & 31;
;       const float4 y = *(const float4*)(ct + row * CT_PITCH + 4 * ch), bv = *(const float4*)(p.b_in + n0 + 4 * ch);
;       uint2 r; r.x = pack2(y.x + bv.x, y.y + bv.y); r.y = pack2(y.z + bv.z, y.w + bv.w);
;       *(uint2*)(dst + (size_t)row * ld + 4 * ch) = r;
;     }
;     return;
.LBB0_104:
	v_lshrrev_b32_e32 v228, 4, v0
	v_and_b32_e32 v229, 15, v0
	v_mul_lo_u32 v227, v228, s86
	v_lshlrev_b32_e32 v226, 5, v229
	v_mul_u32_u24_e32 v228, 0x210, v228
	v_lshlrev_b32_e32 v227, 1, v227
	v_add_u32_e32 v226, v228, v226
	v_lshl_add_u32 v227, v229, 4, v227
	v_lshl_add_u32 v228, v229, 3, s82
	v_lshlrev_b32_e32 v228, 2, v228
	global_load_dwordx4 v[248:251], v228, s[56:57]
	global_load_dwordx4 v[252:255], v228, s[56:57] offset:16
	s_mov_b64 s[98:99], s[84:85]
	s_lshl_b32 s100, s86, 6
	ds_read_b128 v[240:243], v226
	ds_read_b128 v[244:247], v226 offset:16
	s_waitcnt vmcnt(0)
	s_waitcnt lgkmcnt(0)
	v_pk_add_f32 v[240:241], v[240:241], v[248:249]
	v_pk_add_f32 v[242:243], v[242:243], v[250:251]
	v_pk_add_f32 v[244:245], v[244:245], v[252:253]
	v_pk_add_f32 v[246:247], v[246:247], v[254:255]
	v_cvt_pk_bf16_f32 v230, v240, v241
	v_cvt_pk_bf16_f32 v231, v242, v243
	v_cvt_pk_bf16_f32 v232, v244, v245
	v_cvt_pk_bf16_f32 v233, v246, v247
	v_add_u32_e32 v226, 0x4200, v226
	ds_read_b128 v[240:243], v226
	ds_read_b128 v[244:247], v226 offset:16
	global_store_dwordx4 v227, v[230:233], s[98:99]
	s_add_u32 s98, s98, s100
	s_addc_u32 s99, s99, 0
	s_waitcnt lgkmcnt(0)
	v_pk_add_f32 v[240:241], v[240:241], v[248:249]
	v_pk_add_f32 v[242:243], v[242:243], v[250:251]
	v_pk_add_f32 v[244:245], v[244:245], v[252:253]
	v_pk_add_f32 v[246:247], v[246:247], v[254:255]
	v_cvt_pk_bf16_f32 v234, v240, v241
	v_cvt_pk_bf16_f32 v235, v242, v243
	v_cvt_pk_bf16_f32 v236, v244, v245
	v_cvt_pk_bf16_f32 v237, v246, v247
	v_add_u32_e32 v226, 0x4200, v226
	ds_read_b128 v[240:243], v226
	ds_read_b128 v[244:247], v226 offset:16
	global_store_dwordx4 v227, v[234:237], s[98:99]
	s_add_u32 s98, s98, s100
	s_addc_u32 s99, s99, 0
	s_waitcnt lgkmcnt(0)
	v_pk_add_f32 v[240:241], v[240:241], v[248:249]
	v_pk_add_f32 v[242:243], v[242:243], v[250:251]
	v_pk_add_f32 v[244:245], v[244:245], v[252:253]
	v_pk_add_f32 v[246:247], v[246:247], v[254:255]
	v_cvt_pk_bf16_f32 v230, v240, v241
	v_cvt_pk_bf16_f32 v231, v242, v243
	v_cvt_pk_bf16_f32 v232, v244, v245
	v_cvt_pk_bf16_f32 v233, v246, v247
	v_add_u32_e32 v226, 0x4200, v226
	ds_read_b128 v[240:243], v226
	ds_read_b128 v[244:247], v226 offset:16
	global_store_dwordx4 v227, v[230:233], s[98:99]
	s_add_u32 s98, s98, s100
	s_addc_u32 s99, s99, 0
	s_waitcnt lgkmcnt(0)
	v_pk_add_f32 v[240:241], v[240:241], v[248:249]
	v_pk_add_f32 v[242:243], v[242:243], v[250:251]
	v_pk_add_f32 v[244:245], v[244:245], v[252:253]
	v_pk_add_f32 v[246:247], v[246:247], v[254:255]
	v_cvt_pk_bf16_f32 v234, v240, v241
	v_cvt_pk_bf16_f32 v235, v242, v243
	v_cvt_pk_bf16_f32 v236, v244, v245
	v_cvt_pk_bf16_f32 v237, v246, v247
	v_add_u32_e32 v226, 0x4200, v226
	ds_read_b128 v[240:243], v226
	ds_read_b128 v[244:247], v226 offset:16
	global_store_dwordx4 v227, v[234:237], s[98:99]
	s_add_u32 s98, s98, s100
	s_addc_u32 s99, s99, 0
	s_waitcnt lgkmcnt(0)
	v_pk_add_f32 v[240:241], v[240:241], v[248:249]
	v_pk_add_f32 v[242:243], v[242:243], v[250:251]
	v_pk_add_f32 v[244:245], v[244:245], v[252:253]
	v_pk_add_f32 v[246:247], v[246:247], v[254:255]
	v_cvt_pk_bf16_f32 v230, v240, v241
	v_cvt_pk_bf16_f32 v231, v242, v243
	v_cvt_pk_bf16_f32 v232, v244, v245
	v_cvt_pk_bf16_f32 v233, v246, v247
	v_add_u32_e32 v226, 0x4200, v226
	ds_read_b128 v[240:243], v226
	ds_read_b128 v[244:247], v226 offset:16
	global_store_dwordx4 v227, v[230:233], s[98:99]
	s_add_u32 s98, s98, s100
	s_addc_u32 s99, s99, 0
	s_waitcnt lgkmcnt(0)
	v_pk_add_f32 v[240:241], v[240:241], v[248:249]
	v_pk_add_f32 v[242:243], v[242:243], v[250:251]
	v_pk_add_f32 v[244:245], v[244:245], v[252:253]
	v_pk_add_f32 v[246:247], v[246:247], v[254:255]
	v_cvt_pk_bf16_f32 v234, v240, v241
	v_cvt_pk_bf16_f32 v235, v242, v243
	v_cvt_pk_bf16_f32 v236, v244, v245
	v_cvt_pk_bf16_f32 v237, v246, v247
	v_add_u32_e32 v226, 0x4200, v226
	ds_read_b128 v[240:243], v226
	ds_read_b128 v[244:247], v226 offset:16
	global_store_dwordx4 v227, v[234:237], s[98:99]
	s_add_u32 s98, s98, s100
	s_addc_u32 s99, s99, 0
	s_waitcnt lgkmcnt(0)
	v_pk_add_f32 v[240:241], v[240:241], v[248:249]
	v_pk_add_f32 v[242:243], v[242:243], v[250:251]
	v_pk_add_f32 v[244:245], v[244:245], v[252:253]
	v_pk_add_f32 v[246:247], v[246:247], v[254:255]
	v_cvt_pk_bf16_f32 v230, v240, v241
	v_cvt_pk_bf16_f32 v231, v242, v243
	v_cvt_pk_bf16_f32 v232, v244, v245
	v_cvt_pk_bf16_f32 v233, v246, v247
	v_add_u32_e32 v226, 0x4200, v226
	ds_read_b128 v[240:243], v226
	ds_read_b128 v[244:247], v226 offset:16
	global_store_dwordx4 v227, v[230:233], s[98:99]
	s_add_u32 s98, s98, s100
	s_addc_u32 s99, s99, 0
	s_waitcnt lgkmcnt(0)
	v_pk_add_f32 v[240:241], v[240:241], v[248:249]
	v_pk_add_f32 v[242:243], v[242:243], v[250:251]
	v_pk_add_f32 v[244:245], v[244:245], v[252:253]
	v_pk_add_f32 v[246:247], v[246:247], v[254:255]
	v_cvt_pk_bf16_f32 v234, v240, v241
	v_cvt_pk_bf16_f32 v235, v242, v243
	v_cvt_pk_bf16_f32 v236, v244, v245
	v_cvt_pk_bf16_f32 v237, v246, v247
	global_store_dwordx4 v227, v[234:237], s[98:99]
	s_branch .LBB0_59
